# DPP / lane-swap wave reductions (quad_perm, row_half_mirror, row_ror:8, v_permlane16/32_swap) instead of ds_bpermute butterflies in the P1, P7 and P10 row loops; same partners and order, bit-identical
# speedup vs baseline: 1.0102x; 1.0024x over previous
.LBB0_218:
	s_add_i32 s0, s20, 0xfffff000
	s_lshr_b32 s1, s0, 11
	s_mulk_i32 s1, 0x3000
	s_add_i32 s4, s1, 0x3000
	s_cmpk_lt_i32 s20, 0x1000
	s_cselect_b32 s1, s21, 0
	s_cselect_b32 s0, s20, s0
	s_cselect_b32 s33, s37, s39
	s_cselect_b32 s62, s36, s38
	s_cselect_b32 s4, 0, s4
	s_lshl_b64 s[0:1], s[0:1], 13
	s_add_u32 s0, s62, s0
	s_addc_u32 s1, s33, s1
	s_lshl_b64 s[62:63], s[4:5], 2
	s_add_u32 s62, s10, s62
	s_addc_u32 s63, s11, s63
	s_add_u32 s68, s62, 0x2000
	v_lshl_add_u64 v[24:25], s[0:1], 0, v[110:111]
	s_addc_u32 s69, s63, 0
	global_load_dwordx4 v[44:47], v110, s[0:1]
	global_load_dwordx4 v[52:55], v110, s[0:1] offset:1024
	global_load_dwordx4 v[20:23], v[116:117], off
	global_load_dwordx4 v[16:19], v[116:117], off offset:1024
	global_load_dwordx4 v[162:165], v129, s[68:69]
	global_load_dwordx4 v[170:173], v183, s[68:69]
	global_load_dwordx4 v[4:7], v129, s[62:63]
	global_load_dwordx4 v[0:3], v129, s[62:63] offset:1024
	global_load_dwordx4 v[56:59], v110, s[0:1] offset:2048
	global_load_dwordx4 v[64:67], v110, s[0:1] offset:3072
	global_load_dwordx4 v[36:39], v[116:117], off offset:2048
	global_load_dwordx4 v[32:35], v[116:117], off offset:3072
	global_load_dwordx4 v[174:177], v186, s[68:69]
	global_load_dwordx4 v[198:201], v187, s[68:69]
	global_load_dwordx4 v[12:15], v129, s[62:63] offset:2048
	global_load_dwordx4 v[8:11], v129, s[62:63] offset:3072
	s_movk_i32 s0, 0x1000
	v_add_co_u32_e64 v48, s[0:1], s0, v24
	s_nop 1
	v_addc_co_u32_e64 v49, s[0:1], 0, v25, s[0:1]
	global_load_dwordx4 v[202:205], v188, s[68:69]
	global_load_dwordx4 v[24:27], v188, s[62:63]
	global_load_dwordx4 v[84:87], v[48:49], off
	global_load_dwordx4 v[80:83], v[48:49], off offset:1024
	global_load_dwordx4 v[68:71], v[118:119], off
	global_load_dwordx4 v[60:63], v[120:121], off
	global_load_dwordx4 v[104:107], v189, s[68:69]
	global_load_dwordx4 v[28:31], v189, s[62:63]
	global_load_dwordx4 v[100:103], v190, s[68:69]
	global_load_dwordx4 v[40:43], v190, s[62:63]
	global_load_dwordx4 v[92:95], v[48:49], off offset:2048
	global_load_dwordx4 v[88:91], v[48:49], off offset:3072
	global_load_dwordx4 v[76:79], v[122:123], off
	global_load_dwordx4 v[72:75], v[124:125], off
	global_load_dwordx4 v[96:99], v191, s[68:69]
	s_nop 0
	global_load_dwordx4 v[48:51], v191, s[62:63]
	s_waitcnt vmcnt(31)
	v_mov_b32_e32 v142, v45
	s_waitcnt vmcnt(30)
	v_mov_b32_e32 v143, v53
	v_mov_b32_e32 v146, v47
	v_mov_b32_e32 v147, v55
	v_mov_b32_e32 v138, v44
	v_mov_b32_e32 v139, v52
	v_mov_b32_e32 v140, v46
	v_mov_b32_e32 v141, v54
	s_waitcnt vmcnt(23)
	v_pk_mul_f32 v[148:149], v[58:59], v[58:59]
	v_pk_mul_f32 v[144:145], v[56:57], v[56:57]
	v_pk_mul_f32 v[142:143], v[142:143], v[142:143]
	v_pk_mul_f32 v[146:147], v[146:147], v[146:147]
	v_pk_add_f32 v[152:153], v[162:163], 1.0 op_sel_hi:[1,0]
	v_pk_add_f32 v[162:163], v[172:173], 1.0 op_sel_hi:[1,0]
	s_waitcnt vmcnt(19)
	v_pk_add_f32 v[172:173], v[174:175], 1.0 op_sel_hi:[1,0]
	s_waitcnt vmcnt(18)
	v_pk_add_f32 v[174:175], v[200:201], 1.0 op_sel_hi:[1,0]
	s_waitcnt vmcnt(15)
	v_pk_add_f32 v[200:201], v[202:203], 1.0 op_sel_hi:[1,0]
	v_pk_mov_b32 v[202:203], v[144:145], v[148:149] op_sel:[1,0]
	v_mov_b32_e32 v145, v149
	v_pk_fma_f32 v[138:139], v[138:139], v[138:139], v[142:143]
	v_pk_fma_f32 v[140:141], v[140:141], v[140:141], v[146:147]
	v_mul_f32_e32 v156, v65, v65
	v_mul_f32_e32 v158, v67, v67
	v_pk_add_f32 v[142:143], v[202:203], v[144:145]
	v_pk_add_f32 v[138:139], v[138:139], v[140:141]
	s_waitcnt vmcnt(13)
	v_mul_f32_e32 v133, v84, v84
	v_mul_f32_e32 v210, v85, v85
	v_mul_f32_e32 v211, v86, v86
	v_mul_f32_e32 v212, v87, v87
	v_pk_add_f32 v[150:151], v[164:165], 1.0 op_sel_hi:[1,0]
	v_pk_add_f32 v[164:165], v[170:171], 1.0 op_sel_hi:[1,0]
	v_pk_add_f32 v[170:171], v[176:177], 1.0 op_sel_hi:[1,0]
	v_pk_add_f32 v[176:177], v[198:199], 1.0 op_sel_hi:[1,0]
	v_pk_add_f32 v[198:199], v[204:205], 1.0 op_sel_hi:[1,0]
	v_pk_fma_f32 v[148:149], v[64:65], v[64:65], v[156:157] op_sel_hi:[1,1,0]
	v_pk_fma_f32 v[204:205], v[66:67], v[66:67], v[158:159] op_sel_hi:[1,1,0]
	v_pk_add_f32 v[140:141], v[142:143], v[142:143] op_sel:[0,1] op_sel_hi:[1,0]
	v_pk_add_f32 v[138:139], v[138:139], v[138:139] op_sel:[0,1] op_sel_hi:[1,0]
	s_waitcnt vmcnt(12)
	v_pk_mul_f32 v[160:161], v[82:83], v[82:83]
	v_pk_mul_f32 v[154:155], v[80:81], v[80:81]
	v_mov_b32_e32 v149, v211
	v_mov_b32_e32 v205, v212
	v_mov_b32_e32 v141, v210
	v_mov_b32_e32 v139, v133
	v_pk_mov_b32 v[206:207], v[154:155], v[160:161] op_sel:[1,0]
	v_mov_b32_e32 v155, v161
	v_pk_add_f32 v[142:143], v[148:149], v[204:205]
	v_pk_add_f32 v[138:139], v[138:139], v[140:141]
	s_waitcnt vmcnt(5)
	v_mul_f32_e32 v166, v93, v93
	v_mul_f32_e32 v168, v95, v95
	v_pk_add_f32 v[144:145], v[206:207], v[154:155]
	v_pk_add_f32 v[138:139], v[138:139], v[142:143]
	s_waitcnt vmcnt(4)
	v_mul_f32_e32 v213, v88, v88
	v_mul_f32_e32 v214, v89, v89
	v_mul_f32_e32 v215, v90, v90
	v_mul_f32_e32 v216, v91, v91
	v_pk_fma_f32 v[160:161], v[92:93], v[92:93], v[166:167] op_sel_hi:[1,1,0]
	v_pk_fma_f32 v[208:209], v[94:95], v[94:95], v[168:169] op_sel_hi:[1,1,0]
	v_pk_add_f32 v[144:145], v[144:145], v[144:145] op_sel:[0,1] op_sel_hi:[1,0]
	v_pk_add_f32 v[138:139], v[138:139], v[138:139] op_sel:[0,1] op_sel_hi:[1,0]
	v_mov_b32_e32 v161, v215
	v_mov_b32_e32 v209, v216
	v_mov_b32_e32 v145, v214
	v_mov_b32_e32 v139, v213
	v_pk_add_f32 v[146:147], v[160:161], v[208:209]
	v_pk_add_f32 v[138:139], v[138:139], v[144:145]
	v_lshl_add_u64 v[178:179], s[28:29], 0, v[136:137]
	v_pk_add_f32 v[138:139], v[138:139], v[146:147]
	v_add_co_u32_e64 v178, s[0:1], s16, v178
	v_add_f32_e32 v133, v138, v139
	v_lshl_add_u64 v[180:181], s[28:29], 0, v[134:135]
	v_addc_co_u32_e64 v179, s[0:1], 0, v179, s[0:1]
	v_add_co_u32_e64 v180, s[0:1], s17, v180
	s_waitcnt lgkmcnt(0)
	s_nop 1
	v_add_f32_dpp v133, v133, v133 quad_perm:[1,0,3,2] row_mask:0xf bank_mask:0xf
	s_mov_b32 s4, 0x800000
	v_addc_co_u32_e64 v181, s[0:1], 0, v181, s[0:1]
	v_mov_b32_e32 v218, v111
	s_waitcnt lgkmcnt(0)
	s_nop 1
	v_add_f32_dpp v133, v133, v133 quad_perm:[2,3,0,1] row_mask:0xf bank_mask:0xf
	v_mov_b32_e32 v219, v111
	v_pk_add_f32 v[106:107], v[106:107], 1.0 op_sel_hi:[1,0]
	v_pk_add_f32 v[104:105], v[104:105], 1.0 op_sel_hi:[1,0]
	v_pk_add_f32 v[100:101], v[100:101], 1.0 op_sel_hi:[1,0]
	s_waitcnt lgkmcnt(0)
	s_nop 1
	v_add_f32_dpp v133, v133, v133 row_half_mirror row_mask:0xf bank_mask:0xf
	s_waitcnt vmcnt(1)
	v_pk_add_f32 v[96:97], v[96:97], 1.0 op_sel_hi:[1,0]
	v_mov_b32_e32 v220, v111
	v_mov_b32_e32 v221, v111
	v_mov_b32_e32 v222, v111
	s_waitcnt lgkmcnt(0)
	s_nop 1
	v_add_f32_dpp v133, v133, v133 row_ror:8 row_mask:0xf bank_mask:0xf
	v_mov_b32_e32 v223, v111
	v_mov_b32_e32 v224, v111
	v_mov_b32_e32 v225, v111
	v_add_u32_e32 v217, s7, v169
	s_waitcnt lgkmcnt(0)
	v_mov_b32_e32 v138, v133
	s_nop 1
	v_permlane16_swap_b32 v133, v138
	v_add_f32_e32 v133, v133, v138
	s_addk_i32 s7, 0x1010
	s_add_u32 s20, s20, 1
	v_pk_add_f32 v[102:103], v[102:103], 1.0 op_sel_hi:[1,0]
	v_pk_add_f32 v[98:99], v[98:99], 1.0 op_sel_hi:[1,0]
	s_waitcnt lgkmcnt(0)
	v_mov_b32_e32 v138, v133
	s_nop 1
	v_permlane32_swap_b32 v133, v138
	v_add_f32_e32 v133, v133, v138
	v_fmamk_f32 v133, v133, 0x3a000000, v192
	v_mul_f32_e32 v138, 0x4b800000, v133
	v_cmp_gt_f32_e64 s[0:1], s4, v133
	s_addc_u32 s21, s21, 0
	v_lshl_add_u64 v[134:135], v[134:135], 0, s[8:9]
	v_cndmask_b32_e64 v133, v133, v138, s[0:1]
	v_rsq_f32_e32 v133, v133
	v_lshl_add_u64 v[136:137], v[136:137], 0, s[12:13]
	s_cmpk_eq_i32 s7, 0x4040
	v_mul_f32_e32 v138, 0x45800000, v133
	v_cndmask_b32_e64 v138, v133, v138, s[0:1]
	v_pk_mul_f32 v[44:45], v[44:45], v[138:139] op_sel_hi:[1,0]
	v_pk_mul_f32 v[52:53], v[52:53], v[138:139] op_sel_hi:[1,0]
	v_pk_mul_f32 v[20:21], v[20:21], v[44:45]
	v_pk_mul_f32 v[16:17], v[16:17], v[52:53]
	v_pk_fma_f32 v[4:5], v[152:153], v[20:21], v[4:5]
	v_pk_mul_f32 v[46:47], v[46:47], v[138:139] op_sel_hi:[1,0]
	v_cvt_pk_fp8_f32 v218, v4, v5
	v_pk_mul_f32 v[54:55], v[54:55], v[138:139] op_sel_hi:[1,0]
	v_pk_mul_f32 v[56:57], v[56:57], v[138:139] op_sel_hi:[1,0]
	v_pk_mul_f32 v[64:65], v[64:65], v[138:139] op_sel_hi:[1,0]
	v_pk_mul_f32 v[86:87], v[86:87], v[138:139] op_sel_hi:[1,0]
	v_pk_mul_f32 v[84:85], v[84:85], v[138:139] op_sel_hi:[1,0]
	v_pk_mul_f32 v[82:83], v[82:83], v[138:139] op_sel_hi:[1,0]
	v_pk_mul_f32 v[80:81], v[80:81], v[138:139] op_sel_hi:[1,0]
	v_pk_mul_f32 v[92:93], v[92:93], v[138:139] op_sel_hi:[1,0]
	v_pk_mul_f32 v[88:89], v[88:89], v[138:139] op_sel_hi:[1,0]
	v_pk_fma_f32 v[0:1], v[164:165], v[16:17], v[0:1]
	v_pk_mul_f32 v[22:23], v[22:23], v[46:47]
	v_pk_mul_f32 v[18:19], v[18:19], v[54:55]
	v_pk_mul_f32 v[36:37], v[36:37], v[56:57]
	v_pk_mul_f32 v[32:33], v[32:33], v[64:65]
	v_pk_mul_f32 v[44:45], v[68:69], v[84:85]
	v_pk_mul_f32 v[46:47], v[70:71], v[86:87]
	v_pk_mul_f32 v[52:53], v[60:61], v[80:81]
	v_pk_mul_f32 v[54:55], v[62:63], v[82:83]
	v_pk_mul_f32 v[56:57], v[76:77], v[92:93]
	v_pk_mul_f32 v[60:61], v[72:73], v[88:89]
	v_cvt_pk_fp8_f32 v219, v0, v1
	v_pk_fma_f32 v[6:7], v[150:151], v[22:23], v[6:7]
	v_pk_fma_f32 v[2:3], v[162:163], v[18:19], v[2:3]
	v_pk_fma_f32 v[12:13], v[172:173], v[36:37], v[12:13]
	v_pk_fma_f32 v[8:9], v[176:177], v[32:33], v[8:9]
	v_pk_fma_f32 v[16:17], v[198:199], v[46:47], v[26:27]
	v_pk_fma_f32 v[18:19], v[200:201], v[44:45], v[24:25]
	v_pk_fma_f32 v[20:21], v[106:107], v[54:55], v[30:31]
	v_pk_fma_f32 v[22:23], v[104:105], v[52:53], v[28:29]
	v_pk_fma_f32 v[26:27], v[100:101], v[56:57], v[40:41]
	s_waitcnt vmcnt(0)
	v_pk_fma_f32 v[30:31], v[96:97], v[60:61], v[48:49]
	v_cvt_pk_fp8_f32 v220, v12, v13
	v_cvt_pk_fp8_f32 v221, v8, v9
	v_cvt_pk_fp8_f32 v222, v18, v19
	v_cvt_pk_fp8_f32 v223, v22, v23
	v_cvt_pk_fp8_f32 v224, v26, v27
	v_cvt_pk_fp8_f32 v225, v30, v31
	v_cvt_pk_fp8_f32 v218, v6, v7 op_sel:[0,0,1]
	v_pk_mul_f32 v[58:59], v[58:59], v[138:139] op_sel_hi:[1,0]
	v_pk_mul_f32 v[66:67], v[66:67], v[138:139] op_sel_hi:[1,0]
	v_pk_mul_f32 v[94:95], v[94:95], v[138:139] op_sel_hi:[1,0]
	v_pk_mul_f32 v[90:91], v[90:91], v[138:139] op_sel_hi:[1,0]
	v_pk_mul_f32 v[38:39], v[38:39], v[58:59]
	v_pk_mul_f32 v[34:35], v[34:35], v[66:67]
	v_pk_mul_f32 v[58:59], v[78:79], v[94:95]
	v_pk_mul_f32 v[62:63], v[74:75], v[90:91]
	v_cvt_pk_fp8_f32 v219, v2, v3 op_sel:[0,0,1]
	v_pk_fma_f32 v[14:15], v[170:171], v[38:39], v[14:15]
	v_pk_fma_f32 v[10:11], v[174:175], v[34:35], v[10:11]
	v_pk_fma_f32 v[24:25], v[102:103], v[58:59], v[42:43]
	v_pk_fma_f32 v[28:29], v[98:99], v[62:63], v[50:51]
	v_cvt_pk_bf16_f32 v32, v4, v5
	v_cvt_pk_bf16_f32 v33, v6, v7
	v_cvt_pk_bf16_f32 v4, v0, v1
	v_cvt_pk_bf16_f32 v5, v2, v3
	v_cvt_pk_bf16_f32 v0, v12, v13
	v_cvt_pk_bf16_f32 v1, v14, v15
	v_cvt_pk_bf16_f32 v12, v8, v9
	v_cvt_pk_bf16_f32 v13, v10, v11
	v_cvt_pk_bf16_f32 v8, v18, v19
	v_cvt_pk_bf16_f32 v9, v16, v17
	v_cvt_pk_bf16_f32 v18, v22, v23
	v_cvt_pk_bf16_f32 v19, v20, v21
	v_cvt_pk_bf16_f32 v22, v26, v27
	v_cvt_pk_bf16_f32 v23, v24, v25
	v_cvt_pk_bf16_f32 v26, v30, v31
	v_cvt_pk_bf16_f32 v27, v28, v29
	global_store_dwordx2 v[178:179], v[32:33], off sc1
	ds_write2st64_b64 v217, v[32:33], v[4:5] offset1:1
	ds_write2st64_b64 v217, v[0:1], v[12:13] offset0:2 offset1:3
	ds_write2st64_b64 v217, v[8:9], v[18:19] offset0:4 offset1:5
	ds_write2st64_b64 v217, v[22:23], v[26:27] offset0:6 offset1:7
	v_cvt_pk_fp8_f32 v220, v14, v15 op_sel:[0,0,1]
	v_cvt_pk_fp8_f32 v221, v10, v11 op_sel:[0,0,1]
	v_cvt_pk_fp8_f32 v222, v16, v17 op_sel:[0,0,1]
	v_cvt_pk_fp8_f32 v223, v20, v21 op_sel:[0,0,1]
	v_cvt_pk_fp8_f32 v224, v24, v25 op_sel:[0,0,1]
	v_cvt_pk_fp8_f32 v225, v28, v29 op_sel:[0,0,1]
	global_store_dword v[180:181], v218, off sc1
	global_store_dwordx2 v[178:179], v[4:5], off offset:512 sc1
	global_store_dword v[180:181], v219, off offset:256 sc1
	global_store_dwordx2 v[178:179], v[0:1], off offset:1024 sc1
	global_store_dword v[180:181], v220, off offset:512 sc1
	global_store_dwordx2 v[178:179], v[12:13], off offset:1536 sc1
	global_store_dword v[180:181], v221, off offset:768 sc1
	global_store_dwordx2 v[178:179], v[8:9], off offset:2048 sc1
	global_store_dword v[180:181], v222, off offset:1024 sc1
	global_store_dwordx2 v[178:179], v[18:19], off offset:2560 sc1
	global_store_dword v[180:181], v223, off offset:1280 sc1
	global_store_dwordx2 v[178:179], v[22:23], off offset:3072 sc1
	global_store_dword v[180:181], v224, off offset:1536 sc1
	global_store_dwordx2 v[178:179], v[26:27], off offset:3584 sc1
	global_store_dword v[180:181], v225, off offset:1792 sc1
	s_cbranch_scc0 .LBB0_218
	v_mov_b32_e32 v0, 0
	v_mov_b32_e32 v1, v0
	v_mov_b32_e32 v2, v0
	v_mov_b32_e32 v3, v0
	v_mov_b32_e32 v12, v0
	v_mov_b32_e32 v13, v0
	v_mov_b32_e32 v14, v0
	v_mov_b32_e32 v15, v0
	v_mov_b32_e32 v8, v0
	v_mov_b32_e32 v9, v0
	v_mov_b32_e32 v10, v0
	v_mov_b32_e32 v11, v0
	v_mov_b32_e32 v16, v0
	v_mov_b32_e32 v17, v0
	v_mov_b32_e32 v18, v0
	v_mov_b32_e32 v19, v0
	v_mov_b32_e32 v4, v0
	v_mov_b32_e32 v5, v0
	v_mov_b32_e32 v6, v0
	v_mov_b32_e32 v7, v0
	v_mov_b32_e32 v20, v0
	v_mov_b32_e32 v21, v0
	v_mov_b32_e32 v22, v0
	v_mov_b32_e32 v23, v0
	v_mov_b32_e32 v148, v128
	v_ashrrev_i32_e32 v149, 31, v128
	v_lshl_add_u64 v[148:149], v[148:149], 1, v[126:127]
	s_mov_b64 s[0:1], 0x10000
	v_add_u32_e32 v150, 0x10100, v182
	v_lshl_add_u64 v[164:165], v[148:149], 0, s[0:1]
	s_mov_b64 s[0:1], 0x20000
	v_lshl_add_u64 v[170:171], v[148:149], 0, s[0:1]
	global_load_dwordx4 v[28:31], v[148:149], off
	global_load_dwordx4 v[32:35], v[164:165], off
	global_load_dwordx4 v[36:39], v[170:171], off
	global_load_dwordx4 v[40:43], v[148:149], off offset:64
	global_load_dwordx4 v[44:47], v[164:165], off offset:64
	global_load_dwordx4 v[48:51], v[170:171], off offset:64
	global_load_dwordx4 v[136:139], v[148:149], off offset:128
	global_load_dwordx4 v[140:143], v[164:165], off offset:128
	global_load_dwordx4 v[144:147], v[170:171], off offset:128
	global_load_dwordx4 v[160:163], v[148:149], off offset:192
	global_load_dwordx4 v[198:201], v[164:165], off offset:192
	global_load_dwordx4 v[202:205], v[170:171], off offset:192
	global_load_dwordx4 v[206:209], v[148:149], off offset:256
	global_load_dwordx4 v[210:213], v[164:165], off offset:256
	global_load_dwordx4 v[214:217], v[170:171], off offset:256
	global_load_dwordx4 v[218:221], v[148:149], off offset:320
	global_load_dwordx4 v[222:225], v[164:165], off offset:320
	global_load_dwordx4 v[226:229], v[170:171], off offset:320
	global_load_dwordx4 v[230:233], v[148:149], off offset:384
	global_load_dwordx4 v[234:237], v[164:165], off offset:384
	global_load_dwordx4 v[238:241], v[170:171], off offset:384
	s_waitcnt lgkmcnt(0)
	s_barrier
	ds_read_b128 v[24:27], v182
	ds_read_b128 v[152:155], v150
	ds_read_b128 v[178:181], v182 offset:64
	ds_read_b128 v[246:249], v150 offset:64
	s_waitcnt vmcnt(18) lgkmcnt(2)
	v_mfma_f32_16x16x32_bf16 v[0:3], v[24:27], v[28:31], v[0:3]
	v_mfma_f32_16x16x32_bf16 v[16:19], v[152:155], v[28:31], v[16:19]
	v_mfma_f32_16x16x32_bf16 v[12:15], v[24:27], v[32:35], v[12:15]
	v_mfma_f32_16x16x32_bf16 v[4:7], v[152:155], v[32:35], v[4:7]
	v_mfma_f32_16x16x32_bf16 v[8:11], v[24:27], v[36:39], v[8:11]
	v_mfma_f32_16x16x32_bf16 v[20:23], v[152:155], v[36:39], v[20:23]
	global_load_dwordx4 v[28:31], v[148:149], off offset:448
	global_load_dwordx4 v[32:35], v[164:165], off offset:448
	global_load_dwordx4 v[36:39], v[170:171], off offset:448
	ds_read_b128 v[24:27], v182 offset:128
	ds_read_b128 v[152:155], v150 offset:128
	s_waitcnt vmcnt(18) lgkmcnt(2)
	v_mfma_f32_16x16x32_bf16 v[0:3], v[178:181], v[40:43], v[0:3]
	v_mfma_f32_16x16x32_bf16 v[16:19], v[246:249], v[40:43], v[16:19]
	v_mfma_f32_16x16x32_bf16 v[12:15], v[178:181], v[44:47], v[12:15]
	v_mfma_f32_16x16x32_bf16 v[4:7], v[246:249], v[44:47], v[4:7]
	v_mfma_f32_16x16x32_bf16 v[8:11], v[178:181], v[48:51], v[8:11]
	v_mfma_f32_16x16x32_bf16 v[20:23], v[246:249], v[48:51], v[20:23]
	ds_read_b128 v[178:181], v182 offset:192
	ds_read_b128 v[246:249], v150 offset:192
	s_waitcnt vmcnt(15) lgkmcnt(2)
	v_mfma_f32_16x16x32_bf16 v[0:3], v[24:27], v[136:139], v[0:3]
	v_mfma_f32_16x16x32_bf16 v[16:19], v[152:155], v[136:139], v[16:19]
	v_mfma_f32_16x16x32_bf16 v[12:15], v[24:27], v[140:143], v[12:15]
	v_mfma_f32_16x16x32_bf16 v[4:7], v[152:155], v[140:143], v[4:7]
	v_mfma_f32_16x16x32_bf16 v[8:11], v[24:27], v[144:147], v[8:11]
	v_mfma_f32_16x16x32_bf16 v[20:23], v[152:155], v[144:147], v[20:23]
	ds_read_b128 v[24:27], v182 offset:256
	ds_read_b128 v[152:155], v150 offset:256
	s_waitcnt vmcnt(12) lgkmcnt(2)
	v_mfma_f32_16x16x32_bf16 v[0:3], v[178:181], v[160:163], v[0:3]
	v_mfma_f32_16x16x32_bf16 v[16:19], v[246:249], v[160:163], v[16:19]
	v_mfma_f32_16x16x32_bf16 v[12:15], v[178:181], v[198:201], v[12:15]
	v_mfma_f32_16x16x32_bf16 v[4:7], v[246:249], v[198:201], v[4:7]
	v_mfma_f32_16x16x32_bf16 v[8:11], v[178:181], v[202:205], v[8:11]
	v_mfma_f32_16x16x32_bf16 v[20:23], v[246:249], v[202:205], v[20:23]
	ds_read_b128 v[178:181], v182 offset:320
	ds_read_b128 v[246:249], v150 offset:320
	s_waitcnt vmcnt(9) lgkmcnt(2)
	v_mfma_f32_16x16x32_bf16 v[0:3], v[24:27], v[206:209], v[0:3]
	v_mfma_f32_16x16x32_bf16 v[16:19], v[152:155], v[206:209], v[16:19]
	v_mfma_f32_16x16x32_bf16 v[12:15], v[24:27], v[210:213], v[12:15]
	v_mfma_f32_16x16x32_bf16 v[4:7], v[152:155], v[210:213], v[4:7]
	v_mfma_f32_16x16x32_bf16 v[8:11], v[24:27], v[214:217], v[8:11]
	v_mfma_f32_16x16x32_bf16 v[20:23], v[152:155], v[214:217], v[20:23]
	ds_read_b128 v[24:27], v182 offset:384
	ds_read_b128 v[152:155], v150 offset:384
	s_waitcnt vmcnt(6) lgkmcnt(2)
	v_mfma_f32_16x16x32_bf16 v[0:3], v[178:181], v[218:221], v[0:3]
	v_mfma_f32_16x16x32_bf16 v[16:19], v[246:249], v[218:221], v[16:19]
	v_mfma_f32_16x16x32_bf16 v[12:15], v[178:181], v[222:225], v[12:15]
	v_mfma_f32_16x16x32_bf16 v[4:7], v[246:249], v[222:225], v[4:7]
	v_mfma_f32_16x16x32_bf16 v[8:11], v[178:181], v[226:229], v[8:11]
	v_mfma_f32_16x16x32_bf16 v[20:23], v[246:249], v[226:229], v[20:23]
	ds_read_b128 v[178:181], v182 offset:448
	ds_read_b128 v[246:249], v150 offset:448
	s_waitcnt vmcnt(3) lgkmcnt(2)
	v_mfma_f32_16x16x32_bf16 v[0:3], v[24:27], v[230:233], v[0:3]
	v_mfma_f32_16x16x32_bf16 v[16:19], v[152:155], v[230:233], v[16:19]
	v_mfma_f32_16x16x32_bf16 v[12:15], v[24:27], v[234:237], v[12:15]
	v_mfma_f32_16x16x32_bf16 v[4:7], v[152:155], v[234:237], v[4:7]
	v_mfma_f32_16x16x32_bf16 v[8:11], v[24:27], v[238:241], v[8:11]
	v_mfma_f32_16x16x32_bf16 v[20:23], v[152:155], v[238:241], v[20:23]
	s_waitcnt vmcnt(0) lgkmcnt(0)
	v_mfma_f32_16x16x32_bf16 v[0:3], v[178:181], v[28:31], v[0:3]
	v_mfma_f32_16x16x32_bf16 v[16:19], v[246:249], v[28:31], v[16:19]
	v_mfma_f32_16x16x32_bf16 v[12:15], v[178:181], v[32:35], v[12:15]
	v_mfma_f32_16x16x32_bf16 v[4:7], v[246:249], v[32:35], v[4:7]
	v_mfma_f32_16x16x32_bf16 v[8:11], v[178:181], v[36:39], v[8:11]
	v_mfma_f32_16x16x32_bf16 v[20:23], v[246:249], v[36:39], v[20:23]
	s_nop 0
	s_barrier
	ds_write_b32 v193, v0
	ds_write_b32 v193, v1 offset:192
	ds_write_b32 v193, v2 offset:384
	ds_write_b32 v194, v3
	ds_write_b32 v193, v12 offset:64
	ds_write_b32 v193, v13 offset:256
	ds_write_b32 v193, v14 offset:448
	ds_write_b32 v194, v15 offset:64
	ds_write_b32 v193, v8 offset:128
	ds_write_b32 v193, v9 offset:320
	ds_write_b32 v193, v10 offset:512
	ds_write_b32 v194, v11 offset:128
	ds_write_b32 v193, v16 offset:3072
	ds_write_b32 v193, v17 offset:3264
	ds_write_b32 v193, v18 offset:3456
	ds_write_b32 v195, v19
	ds_write_b32 v193, v4 offset:3136
	ds_write_b32 v193, v5 offset:3328
	ds_write_b32 v193, v6 offset:3520
	ds_write_b32 v195, v7 offset:64
	ds_write_b32 v193, v20 offset:3200
	ds_write_b32 v193, v21 offset:3392
	ds_write_b32 v193, v22 offset:3584
	ds_write_b32 v195, v23 offset:128
	s_waitcnt lgkmcnt(0)
	s_barrier
	s_and_saveexec_b64 s[20:21], vcc
	s_cbranch_execz .LBB0_216
	s_lshl_b32 s4, s85, 5
	v_lshl_add_u32 v1, v108, 2, 0
	s_mov_b64 s[62:63], 0
	v_mov_b32_e32 v0, v108
	s_branch .LBB0_224

.LBB0_997:
	s_add_i32 s0, s4, 0xfffff000
	s_lshr_b32 s17, s0, 11
	s_add_i32 s17, s17, 1
	s_cmpk_lt_i32 s4, 0x1000
	s_cselect_b32 s19, s5, 0
	s_cselect_b32 s18, s4, s0
	s_cselect_b32 s0, s37, s39
	s_cselect_b32 s20, s36, s38
	s_cselect_b32 s17, 0, s17
	s_lshl_b64 s[18:19], s[18:19], 13
	s_add_u32 s18, s20, s18
	s_addc_u32 s19, s0, s19
	s_mul_i32 s0, s17, 0x1800
	s_lshl_b64 s[20:21], s[0:1], 2
	s_add_u32 s20, s3, s20
	s_mul_i32 s0, s17, 0x3000
	s_addc_u32 s21, s12, s21
	s_lshl_b64 s[22:23], s[0:1], 2
	s_add_u32 s0, s28, s22
	v_lshl_add_u64 v[160:161], s[28:29], 0, v[130:131]
	s_addc_u32 s17, s29, s23
	s_add_u32 s22, s0, 0x106000
	v_add_co_u32_e32 v52, vcc, s14, v160
	v_lshl_add_u64 v[32:33], s[18:19], 0, v[128:129]
	s_addc_u32 s23, s17, 0
	v_addc_co_u32_e32 v53, vcc, 0, v161, vcc
	s_add_u32 s24, s20, 0x2000
	v_add_co_u32_e32 v54, vcc, s13, v32
	s_addc_u32 s25, s21, 0
	s_nop 0
	v_addc_co_u32_e32 v55, vcc, 0, v33, vcc
	global_load_dwordx4 v[0:3], v180, s[24:25]
	global_load_dwordx4 v[4:7], v180, s[22:23]
	global_load_dwordx4 v[64:67], v128, s[18:19]
	global_load_dwordx4 v[68:71], v128, s[18:19] offset:1024
	global_load_dwordx4 v[76:79], v180, s[20:21]
	global_load_dwordx4 v[72:75], v180, s[20:21] offset:1024
	global_load_dwordx4 v[8:11], v181, s[24:25]
	global_load_dwordx4 v[12:15], v181, s[22:23]
	global_load_dwordx4 v[16:19], v182, s[24:25]
	global_load_dwordx4 v[20:23], v182, s[22:23]
	global_load_dwordx2 v[136:137], v[52:53], off
	global_load_dwordx2 v[138:139], v[52:53], off offset:512
	global_load_dwordx2 v[142:143], v[52:53], off offset:1024
	global_load_dwordx2 v[144:145], v[52:53], off offset:1536
	global_load_dwordx4 v[84:87], v128, s[18:19] offset:2048
	global_load_dwordx4 v[80:83], v128, s[18:19] offset:3072
	global_load_dwordx4 v[92:95], v180, s[20:21] offset:2048
	global_load_dwordx4 v[88:91], v180, s[20:21] offset:3072
	global_load_dwordx4 v[24:27], v183, s[24:25]
	global_load_dwordx4 v[28:31], v183, s[22:23]
	global_load_dwordx4 v[96:99], v186, s[20:21]
	global_load_dwordx4 v[32:35], v186, s[22:23]
	global_load_dwordx4 v[100:103], v[54:55], off
	global_load_dwordx4 v[104:107], v[54:55], off offset:1024
	global_load_dwordx4 v[36:39], v186, s[24:25]
	global_load_dwordx4 v[108:111], v187, s[20:21]
	global_load_dwordx4 v[40:43], v187, s[24:25]
	global_load_dwordx4 v[44:47], v187, s[22:23]
	global_load_dwordx4 v[112:115], v188, s[20:21]
	global_load_dwordx4 v[48:51], v188, s[22:23]
	global_load_dwordx2 v[148:149], v[52:53], off offset:2048
	global_load_dwordx2 v[154:155], v[52:53], off offset:2560
	global_load_dwordx2 v[158:159], v[52:53], off offset:3072
	global_load_dwordx2 v[162:163], v[52:53], off offset:3584
	global_load_dwordx4 v[120:123], v[54:55], off offset:2048
	global_load_dwordx4 v[116:119], v[54:55], off offset:3072
	s_nop 0
	global_load_dwordx4 v[52:55], v188, s[24:25]
	global_load_dwordx4 v[124:127], v189, s[20:21]
	global_load_dwordx4 v[56:59], v189, s[24:25]
	global_load_dwordx4 v[60:63], v189, s[22:23]
	s_waitcnt vmcnt(29)
	v_lshlrev_b32_e32 v134, 16, v136
	v_and_b32_e32 v135, 0xffff0000, v136
	v_lshlrev_b32_e32 v136, 16, v137
	v_and_b32_e32 v137, 0xffff0000, v137
	s_waitcnt vmcnt(28)
	v_lshlrev_b32_e32 v153, 16, v139
	v_lshlrev_b32_e32 v152, 16, v138
	v_and_b32_e32 v139, 0xffff0000, v139
	v_and_b32_e32 v138, 0xffff0000, v138
	s_waitcnt vmcnt(27)
	v_and_b32_e32 v141, 0xffff0000, v142
	s_waitcnt vmcnt(26)
	v_lshlrev_b32_e32 v151, 16, v144
	s_waitcnt vmcnt(6)
	v_lshlrev_b32_e32 v169, 16, v162
	v_mul_f32_e32 v150, v137, v137
	v_pk_mul_f32 v[192:193], v[138:139], v[138:139]
	v_mul_f32_e32 v168, v135, v135
	v_lshlrev_b32_e32 v140, 16, v142
	v_lshlrev_b32_e32 v142, 16, v143
	v_and_b32_e32 v143, 0xffff0000, v143
	v_mov_b32_e32 v195, v151
	v_mul_f32_e32 v194, v141, v141
	v_mov_b32_e32 v206, v152
	v_mov_b32_e32 v207, v138
	v_mov_b32_e32 v138, v153
	v_pk_fma_f32 v[212:213], v[136:137], v[136:137], v[150:151] op_sel_hi:[1,1,0]
	v_pk_fma_f32 v[152:153], v[152:153], v[152:153], v[192:193]
	v_pk_fma_f32 v[192:193], v[134:135], v[134:135], v[168:169] op_sel_hi:[1,1,0]
	v_and_b32_e32 v147, 0xffff0000, v144
	v_lshlrev_b32_e32 v144, 16, v145
	v_and_b32_e32 v145, 0xffff0000, v145
	v_mul_f32_e32 v196, v143, v143
	v_mov_b32_e32 v197, v169
	v_pk_fma_f32 v[214:215], v[140:141], v[140:141], v[194:195] op_sel_hi:[1,1,0]
	v_mov_b32_e32 v150, v192
	v_mov_b32_e32 v194, v212
	v_mul_f32_e32 v223, v147, v147
	v_mul_f32_e32 v224, v144, v144
	v_mul_f32_e32 v225, v145, v145
	v_mov_b32_e32 v146, v151
	v_pk_fma_f32 v[216:217], v[142:143], v[142:143], v[196:197] op_sel_hi:[1,1,0]
	v_pk_add_f32 v[192:193], v[192:193], v[212:213]
	v_pk_add_f32 v[152:153], v[152:153], v[152:153] op_sel:[0,1] op_sel_hi:[1,0]
	v_pk_mul_f32 v[150:151], v[150:151], v[194:195]
	v_lshlrev_b32_e32 v167, 16, v149
	v_lshlrev_b32_e32 v166, 16, v148
	v_and_b32_e32 v149, 0xffff0000, v149
	v_and_b32_e32 v148, 0xffff0000, v148
	v_mov_b32_e32 v215, v224
	v_mov_b32_e32 v217, v225
	v_mov_b32_e32 v153, v223
	v_mov_b32_e32 v193, v151
	v_pk_mul_f32 v[198:199], v[148:149], v[148:149]
	v_pk_add_f32 v[194:195], v[214:215], v[216:217]
	v_pk_add_f32 v[150:151], v[192:193], v[152:153]
	v_lshlrev_b32_e32 v171, 16, v155
	v_lshlrev_b32_e32 v170, 16, v154
	v_and_b32_e32 v155, 0xffff0000, v155
	v_and_b32_e32 v154, 0xffff0000, v154
	v_mov_b32_e32 v208, v166
	v_mov_b32_e32 v209, v148
	v_mov_b32_e32 v148, v167
	v_pk_fma_f32 v[166:167], v[166:167], v[166:167], v[198:199]
	v_pk_add_f32 v[150:151], v[150:151], v[194:195]
	v_lshlrev_b32_e32 v156, 16, v158
	v_and_b32_e32 v157, 0xffff0000, v158
	v_lshlrev_b32_e32 v158, 16, v159
	v_and_b32_e32 v159, 0xffff0000, v159
	v_pk_mul_f32 v[200:201], v[154:155], v[154:155]
	v_pk_add_f32 v[166:167], v[166:167], v[166:167] op_sel:[0,1] op_sel_hi:[1,0]
	v_pk_add_f32 v[150:151], v[150:151], v[150:151] op_sel:[0,1] op_sel_hi:[1,0]
	v_and_b32_e32 v165, 0xffff0000, v162
	v_lshlrev_b32_e32 v162, 16, v163
	v_and_b32_e32 v163, 0xffff0000, v163
	v_mov_b32_e32 v203, 0
	v_mov_b32_e32 v205, 0
	v_mul_f32_e32 v202, v157, v157
	v_mul_f32_e32 v204, v159, v159
	v_mov_b32_e32 v210, v170
	v_mov_b32_e32 v211, v154
	v_mov_b32_e32 v154, v171
	v_pk_fma_f32 v[170:171], v[170:171], v[170:171], v[200:201]
	v_mov_b32_e32 v196, v166
	v_mov_b32_e32 v168, v150
	v_mul_f32_e32 v226, v165, v165
	v_mul_f32_e32 v227, v162, v162
	v_mul_f32_e32 v228, v163, v163
	v_pk_fma_f32 v[198:199], v[156:157], v[156:157], v[202:203] op_sel_hi:[1,1,0]
	v_pk_fma_f32 v[200:201], v[158:159], v[158:159], v[204:205] op_sel_hi:[1,1,0]
	v_pk_add_f32 v[170:171], v[170:171], v[170:171] op_sel:[0,1] op_sel_hi:[1,0]
	v_pk_add_f32 v[150:151], v[150:151], v[166:167]
	v_pk_mul_f32 v[152:153], v[168:169], v[196:197]
	v_mov_b32_e32 v199, v227
	v_mov_b32_e32 v201, v228
	v_mov_b32_e32 v171, v226
	v_mov_b32_e32 v151, v153
	v_pk_add_f32 v[198:199], v[198:199], v[200:201]
	v_pk_add_f32 v[150:151], v[150:151], v[170:171]
	v_add_co_u32_e32 v160, vcc, s16, v160
	v_pk_add_f32 v[150:151], v[150:151], v[198:199]
	s_nop 0
	v_addc_co_u32_e32 v161, vcc, 0, v161, vcc
	v_add_f32_e32 v150, v150, v151
	v_mov_b32_e32 v164, v169
	v_mov_b32_e32 v191, 0
	v_mov_b32_e32 v218, 0
	v_mov_b32_e32 v219, 0
	s_waitcnt lgkmcnt(0)
	s_nop 1
	v_add_f32_dpp v150, v150, v150 quad_perm:[1,0,3,2] row_mask:0xf bank_mask:0xf
	v_mov_b32_e32 v220, 0
	v_mov_b32_e32 v221, 0
	v_mov_b32_e32 v222, 0
	s_add_u32 s4, s4, s34
	s_waitcnt lgkmcnt(0)
	s_nop 1
	v_add_f32_dpp v150, v150, v150 quad_perm:[2,3,0,1] row_mask:0xf bank_mask:0xf
	s_addc_u32 s5, s5, s35
	v_lshl_add_u64 v[172:173], s[28:29], 0, v[132:133]
	v_lshl_add_u64 v[130:131], v[130:131], 0, s[6:7]
	v_lshl_add_u64 v[132:133], v[132:133], 0, s[10:11]
	s_waitcnt lgkmcnt(0)
	s_nop 1
	v_add_f32_dpp v150, v150, v150 row_half_mirror row_mask:0xf bank_mask:0xf
	s_cmpk_lt_i32 s4, 0x2000
	s_waitcnt lgkmcnt(0)
	s_nop 1
	v_add_f32_dpp v150, v150, v150 row_ror:8 row_mask:0xf bank_mask:0xf
	s_waitcnt lgkmcnt(0)
	v_mov_b32_e32 v151, v150
	s_nop 1
	v_permlane16_swap_b32 v150, v151
	v_add_f32_e32 v150, v150, v151
	s_waitcnt lgkmcnt(0)
	v_mov_b32_e32 v151, v150
	s_nop 1
	v_permlane32_swap_b32 v150, v151
	v_add_f32_e32 v150, v150, v151
	v_fmamk_f32 v150, v150, 0x3a000000, v190
	v_mul_f32_e32 v151, 0x4b800000, v150
	v_cmp_gt_f32_e32 vcc, s15, v150
	s_nop 1
	v_cndmask_b32_e32 v150, v150, v151, vcc
	v_rsq_f32_e32 v150, v150
	s_nop 0
	v_mul_f32_e32 v151, 0x45800000, v150
	v_cndmask_b32_e32 v150, v150, v151, vcc
	v_pk_mul_f32 v[134:135], v[150:151], v[134:135] op_sel_hi:[0,1]
	v_pk_mul_f32 v[136:137], v[150:151], v[136:137] op_sel_hi:[0,1]
	v_pk_mul_f32 v[152:153], v[150:151], v[206:207] op_sel_hi:[0,1]
	v_pk_mul_f32 v[138:139], v[150:151], v[138:139] op_sel_hi:[0,1]
	v_pk_mul_f32 v[140:141], v[150:151], v[140:141] op_sel_hi:[0,1]
	v_pk_mul_f32 v[142:143], v[150:151], v[142:143] op_sel_hi:[0,1]
	v_pk_mul_f32 v[146:147], v[146:147], v[150:151] op_sel_hi:[1,0]
	v_pk_mul_f32 v[144:145], v[144:145], v[150:151] op_sel_hi:[1,0]
	v_pk_mul_f32 v[166:167], v[150:151], v[208:209] op_sel_hi:[0,1]
	v_pk_mul_f32 v[148:149], v[150:151], v[148:149] op_sel_hi:[0,1]
	v_pk_mul_f32 v[168:169], v[150:151], v[210:211] op_sel_hi:[0,1]
	v_pk_fma_f32 v[66:67], v[78:79], v[136:137], v[66:67]
	v_pk_fma_f32 v[64:65], v[76:77], v[134:135], v[64:65]
	v_pk_fma_f32 v[70:71], v[74:75], v[138:139], v[70:71]
	v_pk_fma_f32 v[68:69], v[72:73], v[152:153], v[68:69]
	v_pk_mul_f32 v[154:155], v[150:151], v[154:155] op_sel_hi:[0,1]
	v_pk_mul_f32 v[156:157], v[150:151], v[156:157] op_sel_hi:[0,1]
	v_pk_fma_f32 v[72:73], v[94:95], v[142:143], v[86:87]
	v_pk_fma_f32 v[74:75], v[92:93], v[140:141], v[84:85]
	v_pk_fma_f32 v[76:77], v[90:91], v[144:145], v[82:83]
	v_pk_fma_f32 v[78:79], v[88:89], v[146:147], v[80:81]
	v_pk_fma_f32 v[80:81], v[98:99], v[148:149], v[102:103]
	v_pk_fma_f32 v[82:83], v[96:97], v[166:167], v[100:101]
	v_pk_fma_f32 v[86:87], v[108:109], v[168:169], v[104:105]
	v_cvt_pk_bf16_f32 v96, v64, v65
	v_cvt_pk_bf16_f32 v97, v66, v67
	v_cvt_pk_bf16_f32 v98, v68, v69
	v_cvt_pk_bf16_f32 v99, v70, v71
	v_mov_b32_e32 v102, v65
	v_mov_b32_e32 v103, v69
	v_mov_b32_e32 v104, v66
	v_mov_b32_e32 v105, v70
	v_pk_fma_f32 v[84:85], v[110:111], v[154:155], v[106:107]
	s_waitcnt vmcnt(5)
	v_pk_fma_f32 v[90:91], v[112:113], v[156:157], v[120:121]
	v_mov_b32_e32 v100, v64
	v_mov_b32_e32 v101, v68
	v_mov_b32_e32 v106, v67
	v_mov_b32_e32 v107, v71
	v_pk_mul_f32 v[110:111], v[72:73], v[72:73]
	v_pk_mul_f32 v[112:113], v[74:75], v[74:75]
	global_store_dwordx2 v[160:161], v[96:97], off sc1
	global_store_dwordx2 v[160:161], v[98:99], off offset:512 sc1
	v_pk_mul_f32 v[96:97], v[102:103], v[102:103]
	v_pk_mul_f32 v[98:99], v[104:105], v[104:105]
	v_pk_mul_f32 v[158:159], v[150:151], v[158:159] op_sel_hi:[0,1]
	v_pk_mul_f32 v[164:165], v[164:165], v[150:151] op_sel_hi:[1,0]
	v_pk_mul_f32 v[150:151], v[162:163], v[150:151] op_sel_hi:[1,0]
	v_pk_mov_b32 v[102:103], v[112:113], v[110:111] op_sel:[1,0]
	v_mov_b32_e32 v113, v111
	v_pk_fma_f32 v[96:97], v[100:101], v[100:101], v[96:97]
	v_pk_fma_f32 v[98:99], v[106:107], v[106:107], v[98:99]
	s_waitcnt vmcnt(4)
	v_pk_fma_f32 v[92:93], v[126:127], v[150:151], v[118:119]
	v_pk_fma_f32 v[94:95], v[124:125], v[164:165], v[116:117]
	v_cvt_pk_bf16_f32 v108, v74, v75
	v_cvt_pk_bf16_f32 v109, v72, v73
	v_mul_f32_e32 v116, v78, v78
	v_mul_f32_e32 v118, v76, v76
	v_pk_add_f32 v[100:101], v[112:113], v[102:103]
	v_pk_add_f32 v[96:97], v[96:97], v[98:99]
	global_store_dwordx2 v[160:161], v[108:109], off offset:1024 sc1
	v_pk_fma_f32 v[104:105], v[78:79], v[78:79], v[116:117] op_sel_hi:[1,1,0]
	v_pk_fma_f32 v[108:109], v[76:77], v[76:77], v[118:119] op_sel_hi:[1,1,0]
	v_pk_add_f32 v[98:99], v[100:101], v[100:101] op_sel_hi:[0,1]
	v_pk_add_f32 v[96:97], v[96:97], v[96:97] op_sel_hi:[0,1]
	v_pk_mul_f32 v[124:125], v[84:85], v[84:85]
	v_pk_mul_f32 v[126:127], v[86:87], v[86:87]
	v_mul_f32_e32 v104, v82, v82
	v_mul_f32_e32 v108, v83, v83
	v_mul_f32_e32 v98, v81, v81
	v_mul_f32_e32 v96, v80, v80
	v_pk_fma_f32 v[88:89], v[114:115], v[158:159], v[122:123]
	v_pk_mov_b32 v[110:111], v[126:127], v[124:125] op_sel:[1,0]
	v_mov_b32_e32 v127, v125
	v_pk_add_f32 v[100:101], v[104:105], v[108:109]
	v_pk_add_f32 v[96:97], v[98:99], v[96:97]
	v_cvt_pk_bf16_f32 v114, v78, v79
	v_cvt_pk_bf16_f32 v115, v76, v77
	v_mul_f32_e32 v136, v90, v90
	v_mul_f32_e32 v138, v88, v88
	v_pk_add_f32 v[102:103], v[126:127], v[110:111]
	v_pk_add_f32 v[96:97], v[100:101], v[96:97]
	global_store_dwordx2 v[160:161], v[114:115], off offset:1536 sc1
	v_pk_fma_f32 v[114:115], v[90:91], v[90:91], v[136:137] op_sel_hi:[1,1,0]
	v_pk_fma_f32 v[116:117], v[88:89], v[88:89], v[138:139] op_sel_hi:[1,1,0]
	v_pk_add_f32 v[102:103], v[102:103], v[102:103] op_sel_hi:[0,1]
	v_pk_add_f32 v[96:97], v[96:97], v[96:97] op_sel_hi:[0,1]
	v_mul_f32_e32 v114, v94, v94
	v_mul_f32_e32 v116, v95, v95
	v_mul_f32_e32 v102, v93, v93
	v_mul_f32_e32 v96, v92, v92
	v_pk_add_f32 v[104:105], v[114:115], v[116:117]
	v_pk_add_f32 v[96:97], v[102:103], v[96:97]
	v_cvt_pk_bf16_f32 v120, v82, v83
	v_pk_add_f32 v[96:97], v[104:105], v[96:97]
	v_cvt_pk_bf16_f32 v122, v86, v87
	v_add_f32_e32 v96, v96, v97
	v_cvt_pk_bf16_f32 v134, v90, v91
	v_cvt_pk_bf16_f32 v140, v94, v95
	v_cvt_pk_bf16_f32 v121, v80, v81
	v_cvt_pk_bf16_f32 v123, v84, v85
	s_waitcnt lgkmcnt(0)
	s_nop 1
	v_add_f32_dpp v96, v96, v96 quad_perm:[1,0,3,2] row_mask:0xf bank_mask:0xf
	v_cvt_pk_bf16_f32 v135, v88, v89
	v_cvt_pk_bf16_f32 v141, v92, v93
	global_store_dwordx2 v[160:161], v[120:121], off offset:2048 sc1
	global_store_dwordx2 v[160:161], v[122:123], off offset:2560 sc1
	global_store_dwordx2 v[160:161], v[134:135], off offset:3072 sc1
	s_waitcnt lgkmcnt(0)
	s_nop 1
	v_add_f32_dpp v96, v96, v96 quad_perm:[2,3,0,1] row_mask:0xf bank_mask:0xf
	global_store_dwordx2 v[160:161], v[140:141], off offset:3584 sc1
	s_waitcnt lgkmcnt(0)
	s_nop 1
	v_add_f32_dpp v96, v96, v96 row_half_mirror row_mask:0xf bank_mask:0xf
	s_waitcnt lgkmcnt(0)
	s_nop 1
	v_add_f32_dpp v96, v96, v96 row_ror:8 row_mask:0xf bank_mask:0xf
	s_waitcnt lgkmcnt(0)
	v_mov_b32_e32 v97, v96
	s_nop 1
	v_permlane16_swap_b32 v96, v97
	v_add_f32_e32 v96, v96, v97
	s_waitcnt lgkmcnt(0)
	v_mov_b32_e32 v97, v96
	s_nop 1
	v_permlane32_swap_b32 v96, v97
	v_add_f32_e32 v96, v96, v97
	v_fmamk_f32 v96, v96, 0x3a000000, v190
	v_mul_f32_e32 v97, 0x4b800000, v96
	v_cmp_gt_f32_e32 vcc, s15, v96
	s_nop 1
	v_cndmask_b32_e32 v96, v96, v97, vcc
	v_rsq_f32_e32 v96, v96
	s_nop 0
	v_mul_f32_e32 v97, 0x45800000, v96
	v_cndmask_b32_e32 v96, v96, v97, vcc
	v_pk_mul_f32 v[64:65], v[64:65], v[96:97] op_sel_hi:[1,0]
	v_pk_mul_f32 v[66:67], v[66:67], v[96:97] op_sel_hi:[1,0]
	v_pk_mul_f32 v[68:69], v[68:69], v[96:97] op_sel_hi:[1,0]
	v_pk_fma_f32 v[0:1], v[0:1], v[64:65], v[4:5]
	v_pk_mul_f32 v[70:71], v[70:71], v[96:97] op_sel_hi:[1,0]
	v_pk_mul_f32 v[74:75], v[74:75], v[96:97] op_sel_hi:[1,0]
	v_pk_fma_f32 v[2:3], v[2:3], v[66:67], v[6:7]
	v_pk_fma_f32 v[6:7], v[8:9], v[68:69], v[12:13]
	v_cvt_pk_fp8_f32 v191, v0, v1
	v_pk_mul_f32 v[78:79], v[78:79], v[96:97] op_sel_hi:[1,0]
	v_pk_fma_f32 v[4:5], v[10:11], v[70:71], v[14:15]
	v_pk_fma_f32 v[10:11], v[16:17], v[74:75], v[20:21]
	v_cvt_pk_fp8_f32 v203, v6, v7
	v_pk_mul_f32 v[72:73], v[72:73], v[96:97] op_sel_hi:[1,0]
	v_pk_mul_f32 v[76:77], v[76:77], v[96:97] op_sel_hi:[1,0]
	v_pk_mul_f32 v[82:83], v[82:83], v[96:97] op_sel_hi:[1,0]
	v_pk_mul_f32 v[86:87], v[86:87], v[96:97] op_sel_hi:[1,0]
	v_pk_mul_f32 v[90:91], v[90:91], v[96:97] op_sel_hi:[1,0]
	v_pk_mul_f32 v[94:95], v[94:95], v[96:97] op_sel_hi:[1,0]
	v_pk_fma_f32 v[14:15], v[24:25], v[78:79], v[28:29]
	v_cvt_pk_fp8_f32 v205, v10, v11
	v_pk_fma_f32 v[8:9], v[18:19], v[72:73], v[22:23]
	v_pk_fma_f32 v[12:13], v[26:27], v[76:77], v[30:31]
	v_pk_fma_f32 v[18:19], v[36:37], v[82:83], v[32:33]
	v_pk_fma_f32 v[22:23], v[40:41], v[86:87], v[44:45]
	v_pk_fma_f32 v[26:27], v[52:53], v[90:91], v[48:49]
	s_waitcnt vmcnt(8)
	v_pk_fma_f32 v[30:31], v[56:57], v[94:95], v[60:61]
	v_cvt_pk_fp8_f32 v218, v14, v15
	v_cvt_pk_fp8_f32 v219, v18, v19
	v_cvt_pk_fp8_f32 v220, v22, v23
	v_cvt_pk_fp8_f32 v221, v26, v27
	v_cvt_pk_fp8_f32 v222, v30, v31
	v_cvt_pk_fp8_f32 v191, v2, v3 op_sel:[0,0,1]
	v_cvt_pk_fp8_f32 v203, v4, v5 op_sel:[0,0,1]
	v_pk_mul_f32 v[80:81], v[80:81], v[96:97] op_sel_hi:[1,0]
	v_pk_mul_f32 v[84:85], v[84:85], v[96:97] op_sel_hi:[1,0]
	v_pk_mul_f32 v[88:89], v[88:89], v[96:97] op_sel_hi:[1,0]
	v_pk_mul_f32 v[92:93], v[92:93], v[96:97] op_sel_hi:[1,0]
	v_cvt_pk_fp8_f32 v205, v8, v9 op_sel:[0,0,1]
	v_pk_fma_f32 v[16:17], v[38:39], v[80:81], v[34:35]
	v_pk_fma_f32 v[20:21], v[42:43], v[84:85], v[46:47]
	v_pk_fma_f32 v[24:25], v[54:55], v[88:89], v[50:51]
	v_pk_fma_f32 v[28:29], v[58:59], v[92:93], v[62:63]
	v_cvt_pk_fp8_f32 v218, v12, v13 op_sel:[0,0,1]
	v_cvt_pk_fp8_f32 v219, v16, v17 op_sel:[0,0,1]
	v_cvt_pk_fp8_f32 v220, v20, v21 op_sel:[0,0,1]
	v_cvt_pk_fp8_f32 v221, v24, v25 op_sel:[0,0,1]
	v_cvt_pk_fp8_f32 v222, v28, v29 op_sel:[0,0,1]
	global_store_dword v[172:173], v191, off offset:-1024 sc1
	global_store_dword v[172:173], v203, off offset:-768 sc1
	global_store_dword v[172:173], v205, off offset:-512 sc1
	global_store_dword v[172:173], v218, off offset:-256 sc1
	global_store_dword v[172:173], v219, off sc1
	global_store_dword v[172:173], v220, off offset:256 sc1
	global_store_dword v[172:173], v221, off offset:512 sc1
	global_store_dword v[172:173], v222, off offset:768 sc1
	s_cbranch_scc1 .LBB0_997

.LBB0_1323:
	s_waitcnt vmcnt(21)
	v_lshlrev_b32_e32 v148, 16, v138
	v_and_b32_e32 v149, 0xffff0000, v138
	v_lshlrev_b32_e32 v138, 16, v139
	v_and_b32_e32 v139, 0xffff0000, v139
	v_mul_f32_e32 v150, v139, v139
	s_waitcnt vmcnt(20)
	v_lshlrev_b32_e32 v153, 16, v137
	v_lshlrev_b32_e32 v152, 16, v136
	v_and_b32_e32 v137, 0xffff0000, v137
	v_and_b32_e32 v136, 0xffff0000, v136
	s_waitcnt vmcnt(18)
	v_lshlrev_b32_e32 v159, 16, v132
	v_mul_f32_e32 v158, v149, v149
	v_pk_fma_f32 v[150:151], v[138:139], v[138:139], v[150:151] op_sel_hi:[1,1,0]
	v_pk_mul_f32 v[154:155], v[136:137], v[136:137]
	v_pk_fma_f32 v[162:163], v[148:149], v[148:149], v[158:159] op_sel_hi:[1,1,0]
	v_pk_fma_f32 v[154:155], v[152:153], v[152:153], v[154:155]
	v_and_b32_e32 v161, 0xffff0000, v132
	v_mov_b32_e32 v158, v162
	v_mov_b32_e32 v164, v150
	v_mov_b32_e32 v165, v159
	v_mul_f32_e32 v147, v161, v161
	v_pk_add_f32 v[150:151], v[162:163], v[150:151]
	v_pk_mul_f32 v[162:163], v[158:159], v[164:165]
	v_pk_add_f32 v[154:155], v[154:155], v[154:155] op_sel:[0,1] op_sel_hi:[1,0]
	v_lshlrev_b32_e32 v156, 16, v134
	v_and_b32_e32 v157, 0xffff0000, v134
	v_lshlrev_b32_e32 v134, 16, v135
	v_and_b32_e32 v135, 0xffff0000, v135
	v_mov_b32_e32 v151, v163
	v_mov_b32_e32 v155, v147
	v_lshlrev_b32_e32 v132, 16, v133
	v_and_b32_e32 v133, 0xffff0000, v133
	v_pk_add_f32 v[150:151], v[150:151], v[154:155]
	v_mul_f32_e32 v154, v157, v157
	v_mul_f32_e32 v158, v135, v135
	v_mul_f32_e32 v160, v132, v132
	v_mul_f32_e32 v166, v133, v133
	v_pk_fma_f32 v[154:155], v[156:157], v[156:157], v[154:155] op_sel_hi:[1,1,0]
	v_pk_fma_f32 v[162:163], v[134:135], v[134:135], v[158:159] op_sel_hi:[1,1,0]
	v_mov_b32_e32 v155, v160
	v_mov_b32_e32 v163, v166
	v_pk_add_f32 v[154:155], v[154:155], v[162:163]
	s_waitcnt vmcnt(7)
	v_lshlrev_b32_e32 v165, 16, v129
	v_pk_add_f32 v[150:151], v[150:151], v[154:155]
	v_lshlrev_b32_e32 v155, 16, v131
	v_lshlrev_b32_e32 v154, 16, v130
	v_and_b32_e32 v131, 0xffff0000, v131
	v_and_b32_e32 v130, 0xffff0000, v130
	v_pk_mul_f32 v[162:163], v[130:131], v[130:131]
	v_lshlrev_b32_e32 v164, 16, v128
	v_pk_fma_f32 v[162:163], v[154:155], v[154:155], v[162:163]
	v_and_b32_e32 v129, 0xffff0000, v129
	v_pk_add_f32 v[162:163], v[162:163], v[162:163] op_sel:[0,1] op_sel_hi:[1,0]
	v_and_b32_e32 v128, 0xffff0000, v128
	s_waitcnt vmcnt(5)
	v_lshlrev_b32_e32 v171, 16, v124
	v_pk_add_f32 v[150:151], v[150:151], v[150:151] op_sel:[0,1] op_sel_hi:[1,0]
	v_pk_mul_f32 v[166:167], v[128:129], v[128:129]
	v_mov_b32_e32 v170, v150
	v_mov_b32_e32 v174, v162
	v_mov_b32_e32 v175, v171
	v_pk_fma_f32 v[166:167], v[164:165], v[164:165], v[166:167]
	v_and_b32_e32 v173, 0xffff0000, v124
	v_pk_add_f32 v[150:151], v[150:151], v[162:163]
	v_pk_mul_f32 v[162:163], v[170:171], v[174:175]
	v_and_b32_e32 v169, 0xffff0000, v126
	v_mul_f32_e32 v147, v173, v173
	v_mov_b32_e32 v151, v163
	v_pk_add_f32 v[162:163], v[166:167], v[166:167] op_sel:[0,1] op_sel_hi:[1,0]
	v_lshlrev_b32_e32 v168, 16, v126
	v_lshlrev_b32_e32 v126, 16, v127
	v_and_b32_e32 v127, 0xffff0000, v127
	v_mov_b32_e32 v163, v147
	v_mul_f32_e32 v158, v169, v169
	v_lshlrev_b32_e32 v124, 16, v125
	v_and_b32_e32 v125, 0xffff0000, v125
	v_pk_add_f32 v[150:151], v[150:151], v[162:163]
	v_pk_fma_f32 v[162:163], v[168:169], v[168:169], v[158:159] op_sel_hi:[1,1,0]
	v_mul_f32_e32 v158, v127, v127
	v_mul_f32_e32 v160, v124, v124
	v_mul_f32_e32 v172, v125, v125
	v_pk_fma_f32 v[166:167], v[126:127], v[126:127], v[158:159] op_sel_hi:[1,1,0]
	v_mov_b32_e32 v163, v160
	v_mov_b32_e32 v167, v172
	v_pk_add_f32 v[162:163], v[162:163], v[166:167]
	v_mov_b32_e32 v160, v159
	v_pk_add_f32 v[150:151], v[150:151], v[162:163]
	v_lshlrev_b32_e32 v162, 16, v122
	v_add_f32_e32 v147, v150, v151
	v_and_b32_e32 v163, 0xffff0000, v122
	v_lshlrev_b32_e32 v122, 16, v123
	v_and_b32_e32 v123, 0xffff0000, v123
	v_mov_b32_e32 v172, v171
	s_waitcnt lgkmcnt(0)
	s_nop 1
	v_add_f32_dpp v147, v147, v147 quad_perm:[1,0,3,2] row_mask:0xf bank_mask:0xf
	s_waitcnt lgkmcnt(0)
	s_nop 1
	v_add_f32_dpp v147, v147, v147 quad_perm:[2,3,0,1] row_mask:0xf bank_mask:0xf
	s_waitcnt lgkmcnt(0)
	s_nop 1
	v_add_f32_dpp v147, v147, v147 row_half_mirror row_mask:0xf bank_mask:0xf
	s_waitcnt lgkmcnt(0)
	s_nop 1
	v_add_f32_dpp v147, v147, v147 row_ror:8 row_mask:0xf bank_mask:0xf
	s_waitcnt lgkmcnt(0)
	v_mov_b32_e32 v150, v147
	s_nop 1
	v_permlane16_swap_b32 v147, v150
	v_add_f32_e32 v147, v147, v150
	s_waitcnt lgkmcnt(0)
	v_mov_b32_e32 v150, v147
	s_nop 1
	v_permlane32_swap_b32 v147, v150
	v_add_f32_e32 v147, v147, v150
	v_fmamk_f32 v147, v147, 0x3a000000, v146
	v_mul_f32_e32 v150, 0x4b800000, v147
	v_cmp_gt_f32_e32 vcc, s17, v147
	s_nop 1
	v_cndmask_b32_e32 v147, v147, v150, vcc
	v_rsq_f32_e32 v147, v147
	s_nop 0
	v_mul_f32_e32 v150, 0x45800000, v147
	v_cndmask_b32_e32 v150, v147, v150, vcc
	v_pk_mul_f32 v[148:149], v[150:151], v[148:149] op_sel_hi:[0,1]
	v_pk_mul_f32 v[138:139], v[150:151], v[138:139] op_sel_hi:[0,1]
	v_pk_fma_f32 v[62:63], v[62:63], v[138:139], v[122:123]
	v_pk_fma_f32 v[60:61], v[60:61], v[148:149], v[162:163]
	global_store_dwordx4 v[72:73], v[60:63], off offset:-4096 sc1
	s_andn2_b64 vcc, exec, s[12:13]
	s_nop 0
	v_lshlrev_b32_e32 v60, 16, v120
	v_and_b32_e32 v61, 0xffff0000, v120
	v_lshlrev_b32_e32 v62, 16, v121
	v_and_b32_e32 v63, 0xffff0000, v121
	v_mov_b32_e32 v120, v152
	v_mov_b32_e32 v121, v136
	v_mov_b32_e32 v136, v153
	v_pk_mul_f32 v[120:121], v[150:151], v[120:121] op_sel_hi:[0,1]
	v_pk_mul_f32 v[122:123], v[150:151], v[136:137] op_sel_hi:[0,1]
	v_pk_fma_f32 v[58:59], v[58:59], v[122:123], v[62:63]
	v_pk_fma_f32 v[56:57], v[56:57], v[120:121], v[60:61]
	global_store_dwordx4 v[72:73], v[56:59], off offset:-3072 sc1
	v_pk_mul_f32 v[60:61], v[150:151], v[156:157] op_sel_hi:[0,1]
	v_pk_mul_f32 v[62:63], v[150:151], v[134:135] op_sel_hi:[0,1]
	v_lshlrev_b32_e32 v56, 16, v118
	v_and_b32_e32 v57, 0xffff0000, v118
	v_lshlrev_b32_e32 v58, 16, v119
	v_and_b32_e32 v59, 0xffff0000, v119
	v_pk_fma_f32 v[54:55], v[54:55], v[62:63], v[58:59]
	v_pk_fma_f32 v[52:53], v[52:53], v[60:61], v[56:57]
	global_store_dwordx4 v[72:73], v[52:55], off offset:-2048 sc1
	v_pk_mul_f32 v[56:57], v[160:161], v[150:151] op_sel_hi:[1,0]
	v_pk_mul_f32 v[58:59], v[132:133], v[150:151] op_sel_hi:[1,0]
	v_lshlrev_b32_e32 v52, 16, v116
	v_and_b32_e32 v53, 0xffff0000, v116
	v_lshlrev_b32_e32 v54, 16, v117
	v_and_b32_e32 v55, 0xffff0000, v117
	v_pk_fma_f32 v[50:51], v[50:51], v[58:59], v[54:55]
	v_pk_fma_f32 v[48:49], v[48:49], v[56:57], v[52:53]
	v_mov_b32_e32 v52, v154
	v_mov_b32_e32 v53, v130
	v_mov_b32_e32 v130, v155
	global_store_dwordx4 v[72:73], v[48:51], off offset:-1024 sc1
	v_pk_mul_f32 v[52:53], v[150:151], v[52:53] op_sel_hi:[0,1]
	v_pk_mul_f32 v[54:55], v[150:151], v[130:131] op_sel_hi:[0,1]
	s_waitcnt vmcnt(8)
	v_lshlrev_b32_e32 v48, 16, v114
	v_and_b32_e32 v49, 0xffff0000, v114
	v_lshlrev_b32_e32 v50, 16, v115
	v_and_b32_e32 v51, 0xffff0000, v115
	v_pk_fma_f32 v[46:47], v[46:47], v[54:55], v[50:51]
	v_pk_fma_f32 v[44:45], v[44:45], v[52:53], v[48:49]
	v_mov_b32_e32 v48, v164
	v_mov_b32_e32 v49, v128
	v_mov_b32_e32 v128, v165
	global_store_dwordx4 v[72:73], v[44:47], off sc1
	v_pk_mul_f32 v[48:49], v[150:151], v[48:49] op_sel_hi:[0,1]
	v_pk_mul_f32 v[50:51], v[150:151], v[128:129] op_sel_hi:[0,1]
	s_waitcnt vmcnt(8)
	v_lshlrev_b32_e32 v44, 16, v112
	v_and_b32_e32 v45, 0xffff0000, v112
	v_lshlrev_b32_e32 v46, 16, v113
	v_and_b32_e32 v47, 0xffff0000, v113
	v_pk_fma_f32 v[42:43], v[42:43], v[50:51], v[46:47]
	v_pk_fma_f32 v[40:41], v[40:41], v[48:49], v[44:45]
	global_store_dwordx4 v[72:73], v[40:43], off offset:1024 sc1
	v_pk_mul_f32 v[44:45], v[150:151], v[168:169] op_sel_hi:[0,1]
	v_pk_mul_f32 v[46:47], v[150:151], v[126:127] op_sel_hi:[0,1]
	s_waitcnt vmcnt(8)
	v_lshlrev_b32_e32 v40, 16, v110
	v_and_b32_e32 v41, 0xffff0000, v110
	v_lshlrev_b32_e32 v42, 16, v111
	v_and_b32_e32 v43, 0xffff0000, v111
	v_pk_fma_f32 v[38:39], v[38:39], v[46:47], v[42:43]
	v_pk_fma_f32 v[36:37], v[36:37], v[44:45], v[40:41]
	global_store_dwordx4 v[72:73], v[36:39], off offset:2048 sc1
	v_pk_mul_f32 v[40:41], v[172:173], v[150:151] op_sel_hi:[1,0]
	v_pk_mul_f32 v[42:43], v[124:125], v[150:151] op_sel_hi:[1,0]
	s_waitcnt vmcnt(8)
	v_lshlrev_b32_e32 v36, 16, v108
	v_and_b32_e32 v37, 0xffff0000, v108
	v_lshlrev_b32_e32 v38, 16, v109
	v_and_b32_e32 v39, 0xffff0000, v109
	s_waitcnt vmcnt(7)
	v_pk_fma_f32 v[34:35], v[34:35], v[42:43], v[38:39]
	v_pk_fma_f32 v[32:33], v[32:33], v[40:41], v[36:37]
	global_store_dwordx4 v[72:73], v[32:35], off offset:3072 sc1
	s_cbranch_vccnz .LBB0_1320
	v_and_b32_e32 v39, 0xffff0000, v82
	v_and_b32_e32 v38, 0xffff0000, v80
	v_and_b32_e32 v43, 0xffff0000, v83
	v_and_b32_e32 v42, 0xffff0000, v81
	v_lshlrev_b32_e32 v37, 16, v82
	v_lshlrev_b32_e32 v36, 16, v80
	v_lshlrev_b32_e32 v41, 16, v83
	v_lshlrev_b32_e32 v40, 16, v81
	v_pk_mul_f32 v[32:33], v[38:39], v[38:39]
	v_pk_mul_f32 v[34:35], v[42:43], v[42:43]
	v_pk_fma_f32 v[32:33], v[36:37], v[36:37], v[32:33]
	v_pk_fma_f32 v[34:35], v[40:41], v[40:41], v[34:35]
	v_and_b32_e32 v47, 0xffff0000, v79
	v_pk_add_f32 v[32:33], v[32:33], v[34:35]
	v_and_b32_e32 v46, 0xffff0000, v78
	v_pk_add_f32 v[32:33], v[32:33], v[32:33] op_sel_hi:[0,1]
	v_lshlrev_b32_e32 v45, 16, v79
	v_lshlrev_b32_e32 v44, 16, v78
	v_pk_mul_f32 v[34:35], v[46:47], v[46:47]
	v_lshlrev_b32_e32 v48, 16, v76
	v_and_b32_e32 v49, 0xffff0000, v76
	v_lshlrev_b32_e32 v54, 16, v77
	v_lshlrev_b32_e32 v50, 16, v96
	v_pk_fma_f32 v[34:35], v[44:45], v[44:45], v[34:35]
	v_mul_f32_e32 v51, v48, v48
	v_mul_f32_e32 v53, v49, v49
	v_and_b32_e32 v55, 0xffff0000, v77
	v_mul_f32_e32 v32, v54, v54
	v_mov_b32_e32 v52, v50
	v_pk_add_f32 v[34:35], v[34:35], v[34:35] op_sel_hi:[0,1]
	v_pk_fma_f32 v[56:57], v[54:55], v[54:55], v[32:33] op_sel_hi:[1,1,0]
	v_and_b32_e32 v120, 0xffff0000, v96
	v_lshlrev_b32_e32 v58, 16, v97
	v_and_b32_e32 v59, 0xffff0000, v97
	v_pk_add_f32 v[52:53], v[50:51], v[52:53]
	v_mul_f32_e32 v56, v120, v120
	v_mul_f32_e32 v34, v58, v58
	v_mul_f32_e32 v32, v59, v59
	v_mul_f32_e32 v60, v50, v50
	v_mov_b32_e32 v61, v53
	v_pk_add_f32 v[52:53], v[60:61], v[56:57]
	v_pk_add_f32 v[32:33], v[34:35], v[32:33]
	v_and_b32_e32 v57, 0xffff0000, v95
	v_pk_add_f32 v[32:33], v[52:53], v[32:33]
	v_and_b32_e32 v56, 0xffff0000, v94
	v_pk_add_f32 v[32:33], v[32:33], v[32:33] op_sel_hi:[0,1]
	v_lshlrev_b32_e32 v53, 16, v95
	v_lshlrev_b32_e32 v52, 16, v94
	v_pk_mul_f32 v[34:35], v[56:57], v[56:57]
	v_lshlrev_b32_e32 v60, 16, v92
	v_and_b32_e32 v61, 0xffff0000, v92
	v_lshlrev_b32_e32 v110, 16, v93
	v_lshlrev_b32_e32 v62, 16, v98
	v_pk_fma_f32 v[34:35], v[52:53], v[52:53], v[34:35]
	v_mul_f32_e32 v63, v60, v60
	v_mul_f32_e32 v109, v61, v61
	v_and_b32_e32 v111, 0xffff0000, v93
	v_mul_f32_e32 v32, v110, v110
	v_mov_b32_e32 v108, v62
	v_pk_add_f32 v[34:35], v[34:35], v[34:35] op_sel_hi:[0,1]
	v_pk_fma_f32 v[112:113], v[110:111], v[110:111], v[32:33] op_sel_hi:[1,1,0]
	v_and_b32_e32 v121, 0xffff0000, v98
	v_lshlrev_b32_e32 v114, 16, v99
	v_and_b32_e32 v115, 0xffff0000, v99
	v_pk_add_f32 v[108:109], v[62:63], v[108:109]
	v_mul_f32_e32 v112, v121, v121
	v_mul_f32_e32 v34, v114, v114
	v_mul_f32_e32 v32, v115, v115
	v_mul_f32_e32 v116, v62, v62
	v_mov_b32_e32 v117, v109
	v_pk_add_f32 v[108:109], v[116:117], v[112:113]
	v_pk_add_f32 v[32:33], v[34:35], v[32:33]
	s_ashr_i32 s11, s10, 31
	v_pk_add_f32 v[32:33], v[108:109], v[32:33]
	v_mov_b32_e32 v116, v37
	v_add_f32_e32 v32, v32, v33
	v_mov_b32_e32 v117, v39
	v_mov_b32_e32 v118, v41
	v_mov_b32_e32 v119, v43
	s_lshl_b64 s[10:11], s[10:11], 13
	s_waitcnt lgkmcnt(0)
	s_nop 1
	v_add_f32_dpp v32, v32, v32 quad_perm:[1,0,3,2] row_mask:0xf bank_mask:0xf
	v_lshlrev_b32_e32 v34, 16, v91
	v_and_b32_e32 v35, 0xffff0000, v91
	v_lshl_add_u64 v[108:109], v[70:71], 0, s[10:11]
	v_mov_b32_e32 v37, v38
	s_waitcnt lgkmcnt(0)
	s_nop 1
	v_add_f32_dpp v32, v32, v32 quad_perm:[2,3,0,1] row_mask:0xf bank_mask:0xf
	v_mov_b32_e32 v41, v42
	v_mov_b32_e32 v51, v120
	v_mov_b32_e32 v63, v121
	s_waitcnt lgkmcnt(0)
	s_nop 1
	v_add_f32_dpp v32, v32, v32 row_half_mirror row_mask:0xf bank_mask:0xf
	s_waitcnt lgkmcnt(0)
	s_nop 1
	v_add_f32_dpp v32, v32, v32 row_ror:8 row_mask:0xf bank_mask:0xf
	s_waitcnt lgkmcnt(0)
	v_mov_b32_e32 v33, v32
	s_nop 1
	v_permlane16_swap_b32 v32, v33
	v_add_f32_e32 v32, v32, v33
	s_waitcnt lgkmcnt(0)
	v_mov_b32_e32 v33, v32
	s_nop 1
	v_permlane32_swap_b32 v32, v33
	v_add_f32_e32 v32, v32, v33
	v_fmamk_f32 v32, v32, 0x3a000000, v146
	v_mul_f32_e32 v33, 0x4b800000, v32
	v_cmp_gt_f32_e32 vcc, s17, v32
	s_nop 1
	v_cndmask_b32_e32 v32, v32, v33, vcc
	v_rsq_f32_e32 v32, v32
	s_nop 0
	v_mul_f32_e32 v33, 0x45800000, v32
	v_cndmask_b32_e32 v112, v32, v33, vcc
	v_lshlrev_b32_e32 v32, 16, v90
	v_and_b32_e32 v33, 0xffff0000, v90
	v_pk_mul_f32 v[116:117], v[116:117], v[112:113] op_sel_hi:[1,0]
	v_pk_mul_f32 v[118:119], v[118:119], v[112:113] op_sel_hi:[1,0]
	v_pk_fma_f32 v[32:33], v[12:13], v[116:117], v[32:33]
	v_pk_fma_f32 v[34:35], v[14:15], v[118:119], v[34:35]
	global_store_dwordx4 v[108:109], v[32:35], off sc1
	v_pk_mul_f32 v[36:37], v[36:37], v[112:113] op_sel_hi:[1,0]
	v_pk_mul_f32 v[38:39], v[40:41], v[112:113] op_sel_hi:[1,0]
	v_lshlrev_b32_e32 v32, 16, v88
	v_and_b32_e32 v33, 0xffff0000, v88
	v_lshlrev_b32_e32 v34, 16, v89
	v_and_b32_e32 v35, 0xffff0000, v89
	v_pk_fma_f32 v[34:35], v[2:3], v[38:39], v[34:35]
	v_pk_fma_f32 v[32:33], v[0:1], v[36:37], v[32:33]
	v_mov_b32_e32 v36, v44
	v_mov_b32_e32 v37, v46
	v_mov_b32_e32 v46, v45
	global_store_dwordx4 v[108:109], v[32:35], off offset:1024 sc1
	v_pk_mul_f32 v[36:37], v[112:113], v[36:37] op_sel_hi:[0,1]
	v_pk_mul_f32 v[38:39], v[112:113], v[46:47] op_sel_hi:[0,1]
	v_lshlrev_b32_e32 v32, 16, v86
	v_and_b32_e32 v33, 0xffff0000, v86
	v_lshlrev_b32_e32 v34, 16, v87
	v_and_b32_e32 v35, 0xffff0000, v87
	v_pk_fma_f32 v[34:35], v[6:7], v[38:39], v[34:35]
	v_pk_fma_f32 v[32:33], v[4:5], v[36:37], v[32:33]
	global_store_dwordx4 v[108:109], v[32:35], off offset:2048 sc1
	v_pk_mul_f32 v[36:37], v[48:49], v[112:113] op_sel_hi:[1,0]
	v_pk_mul_f32 v[38:39], v[54:55], v[112:113] op_sel_hi:[1,0]
	v_lshlrev_b32_e32 v32, 16, v84
	v_and_b32_e32 v33, 0xffff0000, v84
	v_lshlrev_b32_e32 v34, 16, v85
	v_and_b32_e32 v35, 0xffff0000, v85
	v_pk_fma_f32 v[34:35], v[10:11], v[38:39], v[34:35]
	v_pk_fma_f32 v[32:33], v[8:9], v[36:37], v[32:33]
	global_store_dwordx4 v[108:109], v[32:35], off offset:3072 sc1
	v_pk_mul_f32 v[36:37], v[50:51], v[112:113] op_sel_hi:[1,0]
	v_pk_mul_f32 v[38:39], v[58:59], v[112:113] op_sel_hi:[1,0]
	v_lshlrev_b32_e32 v32, 16, v106
	v_and_b32_e32 v33, 0xffff0000, v106
	v_lshlrev_b32_e32 v34, 16, v107
	v_and_b32_e32 v35, 0xffff0000, v107
	v_pk_fma_f32 v[32:33], v[16:17], v[36:37], v[32:33]
	v_add_co_u32_e32 v36, vcc, s18, v108
	v_pk_fma_f32 v[34:35], v[18:19], v[38:39], v[34:35]
	s_nop 0
	v_addc_co_u32_e32 v37, vcc, 0, v109, vcc
	v_mov_b32_e32 v38, v52
	v_mov_b32_e32 v39, v56
	v_mov_b32_e32 v56, v53
	global_store_dwordx4 v[36:37], v[32:35], off sc1
	v_pk_mul_f32 v[38:39], v[112:113], v[38:39] op_sel_hi:[0,1]
	v_pk_mul_f32 v[40:41], v[112:113], v[56:57] op_sel_hi:[0,1]
	v_lshlrev_b32_e32 v32, 16, v104
	v_and_b32_e32 v33, 0xffff0000, v104
	v_lshlrev_b32_e32 v34, 16, v105
	v_and_b32_e32 v35, 0xffff0000, v105
	v_pk_fma_f32 v[34:35], v[22:23], v[40:41], v[34:35]
	v_pk_fma_f32 v[32:33], v[20:21], v[38:39], v[32:33]
	global_store_dwordx4 v[36:37], v[32:35], off offset:1024 sc1
	v_pk_mul_f32 v[38:39], v[60:61], v[112:113] op_sel_hi:[1,0]
	v_pk_mul_f32 v[40:41], v[110:111], v[112:113] op_sel_hi:[1,0]
	v_lshlrev_b32_e32 v32, 16, v102
	v_and_b32_e32 v33, 0xffff0000, v102
	v_lshlrev_b32_e32 v34, 16, v103
	v_and_b32_e32 v35, 0xffff0000, v103
	v_pk_fma_f32 v[34:35], v[30:31], v[40:41], v[34:35]
	v_pk_fma_f32 v[32:33], v[28:29], v[38:39], v[32:33]
	global_store_dwordx4 v[36:37], v[32:35], off offset:2048 sc1
	v_pk_mul_f32 v[38:39], v[62:63], v[112:113] op_sel_hi:[1,0]
	v_pk_mul_f32 v[40:41], v[114:115], v[112:113] op_sel_hi:[1,0]
	v_lshlrev_b32_e32 v32, 16, v100
	v_and_b32_e32 v33, 0xffff0000, v100
	v_lshlrev_b32_e32 v34, 16, v101
	v_and_b32_e32 v35, 0xffff0000, v101
	v_pk_fma_f32 v[34:35], v[26:27], v[40:41], v[34:35]
	v_pk_fma_f32 v[32:33], v[24:25], v[38:39], v[32:33]
	global_store_dwordx4 v[36:37], v[32:35], off offset:3072 sc1
	s_branch .LBB0_1320
